# pooldiff fused with the pool GEMM phase: each workgroup computes the D block its own tile consumes; workgroup barrier instead of grid barrier
# speedup vs baseline: 1.0543x; 1.0099x over previous
.LBB0_824:
	s_cmp_lt_i32 s84, 8
	s_cselect_b64 s[4:5], -1, 0
	s_and_b64 s[8:9], s[4:5], s[0:1]
	s_andn2_b64 vcc, exec, s[8:9]
	s_cbranch_vccnz .LBB0_1116
	v_readlane_b32 s0, v255, 10
	s_cmpk_gt_i32 s0, 0xff
	s_cbranch_scc1 .LBB0_1111
	s_add_u32 s3, s88, 0x290000
	v_readlane_b32 s6, v255, 0
	v_readlane_b32 s74, v255, 10
	s_addc_u32 s7, s89, 0
	s_movk_i32 s0, 0x140
	s_bfe_u32 s74, s74, 0x20003
	v_cmp_gt_u32_e64 s[4:5], s0, v170
	s_lshl_b32 s0, s74, 10
	s_add_i32 s0, s0, 0
	s_lshl_b32 s12, s74, 9
	v_lshl_add_u32 v154, v242, 4, s0
	s_add_u32 s0, s10, s12
	v_mov_b32_e32 v2, 0
	s_addc_u32 s1, s11, 0
	v_lshlrev_b32_e32 v142, 3, v242
	v_mov_b32_e32 v143, v2
	v_lshl_add_u64 v[144:145], s[0:1], 0, v[142:143]
	s_lshl_b32 s0, s91, 3
	v_mov_b32_e32 v173, v2
	s_and_b32 s75, s0, 8
	s_lshl_b32 s75, s75, 2
	v_lshl_add_u64 v[4:5], s[72:73], 0, v[172:173]
	s_mov_b64 s[0:1], 0x1000
	v_lshl_add_u64 v[146:147], v[4:5], 0, s[0:1]
	v_lshl_add_u64 v[4:5], s[88:89], 0, v[172:173]
	s_mov_b64 s[0:1], 0x1cc000
	v_lshl_add_u64 v[148:149], v[4:5], 0, s[0:1]
	s_lshr_b32 s0, s91, 1
	s_mul_i32 s0, s0, 0x140
	s_and_b32 s6, s91, 1
	s_lshl_b32 s6, s6, 7
	s_add_i32 s6, s6, s0
	s_addk_i32 s6, 0x2000
	s_add_u32 s76, s88, s12
	v_readlane_b32 s95, v255, 10
	s_mov_b32 s13, 0
	v_add_u32_e32 v155, -15, v170
	v_add_u32_e32 v156, 0, v172
	v_add_u32_e32 v157, 0xfffffe00, v170
	s_lshr_b32 s0, s95, 5
	s_lshl_b32 s0, s0, 3
	s_and_b32 s1, s95, 7
	s_add_i32 s0, s0, s1
	s_lshl_b32 s0, s0, 2
	s_lshr_b32 s1, s91, 1
	s_add_i32 s95, s0, s1
	s_addc_u32 s77, s89, 0
	s_sub_i32 s78, s75, 32
	s_lshl_b32 s79, s95, 6
	s_lshl_b32 s80, s33, 6
	v_mov_b32_e32 v158, 0x6000
	s_mov_b64 s[14:15], 0x800
	v_mov_b32_e32 v159, 0x358637bd
	s_mov_b32 s81, 0x800000
	s_brev_b32 s94, 48
	s_branch .LBB0_828

.LBB0_829:
	global_load_dword v1, v[6:7], off
	global_load_dword v8, v[6:7], off offset:2048
	global_load_dword v10, v[4:5], off
	global_load_dword v11, v[4:5], off offset:2048
	v_add_co_u32_e32 v6, vcc, 0x1000, v4
	s_nop 1
	v_addc_co_u32_e32 v7, vcc, 0, v5, vcc
	global_load_dword v9, v[6:7], off
	global_load_dword v6, v[6:7], off offset:2048
	s_and_b32 s12, s95, 0xfffffffc
	s_lshl_b32 s12, s12, 6
	s_and_b32 s12, s12, 0x1fc0
	v_mul_u32_u24_e32 v5, 0xcccd, v170
	v_lshrrev_b32_e32 v5, 22, v5
	v_lshlrev_b32_e32 v5, 4, v5
	v_add_u32_e32 v4, s12, v155
	v_sub_u32_e32 v4, v4, v5
	v_mov_b32_e32 v5, v2
	v_cmp_lt_i32_e32 vcc, -1, v4
	s_lshl_b64 s[20:21], s[0:1], 15
	s_add_u32 s20, s3, s20
	s_addc_u32 s21, s7, s21
	s_and_b64 s[18:19], vcc, s[4:5]
	v_lshl_add_u64 v[4:5], v[4:5], 2, s[20:21]
	s_and_saveexec_b64 s[16:17], s[18:19]
	global_load_dword v7, v[4:5], off
	s_or_b64 exec, exec, s[16:17]
	s_waitcnt vmcnt(1)
	v_add_f32_e32 v9, 1.0, v9
	v_mul_f32_e32 v1, v1, v9
	ds_write2st64_b32 v3, v1, v10 offset1:16
	v_add_f32_e32 v6, 1.0, v6
	v_mul_f32_e32 v8, v8, v6
	v_add_u32_e32 v3, 0x800, v3
	ds_write2st64_b32 v3, v8, v11 offset1:16
	v_mov_b32_e32 v3, 0
	s_and_saveexec_b64 s[16:17], s[18:19]
	s_waitcnt vmcnt(0)
	v_fmamk_f32 v1, v7, 0x3a800000, v159
	v_mul_f32_e32 v3, 0x4b800000, v1
	v_cmp_gt_f32_e32 vcc, s81, v1
	s_nop 1
	v_cndmask_b32_e32 v1, v1, v3, vcc
	v_rsq_f32_e32 v1, v1
	s_nop 0
	v_mul_f32_e32 v3, 0x45800000, v1
	v_cndmask_b32_e32 v3, v1, v3, vcc
	s_or_b64 exec, exec, s[16:17]
	s_and_saveexec_b64 s[16:17], s[4:5]
	ds_write_b32 v156, v3 offset:8192

.LBB0_1116:
	s_cmp_gt_i32 s85, 8
	s_cselect_b64 s[0:1], -1, 0
	s_and_b64 s[4:5], s[8:9], s[0:1]
	s_andn2_b64 vcc, exec, s[4:5]
	s_cbranch_vccnz .LBB0_1184
	s_waitcnt vmcnt(0)
	s_barrier
	s_branch .LBB0_1183
	s_cmp_eq_u32 s86, 0
	s_cbranch_scc1 .LBB0_1129
	v_lshrrev_b32_e32 v1, 20, v0
	v_lshrrev_b32_e32 v2, 10, v0
	v_or_b32_e32 v1, v2, v1
	s_movk_i32 s3, 0x3ff
	v_and_or_b32 v1, v1, s3, v170
	v_cmp_eq_u32_e32 vcc, 0, v1
	s_waitcnt lgkmcnt(0)
	s_barrier
	s_and_saveexec_b64 s[4:5], vcc
	s_cbranch_execz .LBB0_1128
	v_readlane_b32 s6, v255, 1
	v_readlane_b32 s7, v255, 2
	buffer_wbl2 sc1
	s_waitcnt vmcnt(0)
	s_load_dwordx2 s[8:9], s[6:7], 0x58
	v_mov_b32_e32 v4, 0
	s_mov_b64 s[12:13], exec
	v_mbcnt_lo_u32_b32 v1, s12, 0
	v_mbcnt_hi_u32_b32 v3, s13, v1
	s_waitcnt lgkmcnt(0)
	global_load_dword v2, v4, s[8:9] offset:40
	v_cmp_eq_u32_e32 vcc, 0, v3
	s_and_saveexec_b64 s[14:15], vcc
	s_cbranch_execz .LBB0_1121
	s_bcnt1_i32_b64 s3, s[12:13]
	v_mov_b32_e32 v1, s3
	global_atomic_add v5, v4, v1, s[8:9] offset:32 sc0
